# phase 0: conversion-item start index rotated by 1792 waves so the workgroups that carry two mod-table tasks (0-31) fall in the 9-item group instead of the 10-item group (on keep_v8)
# speedup vs baseline: 1.0056x; 1.0056x over previous
.LBB0_44:
	s_lshl_b32 s2, s8, 3
	s_waitcnt lgkmcnt(0)
	s_lshl_b32 s10, s33, 3
	s_add_i32 s11, s20, s2
	s_cmpk_lg_u32 s10, 0x800
	s_cbranch_scc1 .Lcv_norot
	s_addk_i32 s11, 0x700
	s_and_b32 s11, s11, 0x7ff
.Lcv_norot:
	v_writelane_b32 v255, s2, 1
	s_cmpk_gt_i32 s11, 0x4eef
	s_barrier
	s_cbranch_scc1 .LBB0_91
	v_and_b32_e32 v22, 31, v1
	v_lshlrev_b32_e32 v1, 3, v28
	v_and_b32_e32 v8, 56, v1
	v_mov_b32_e32 v5, 0
	v_lshlrev_b32_e32 v4, 1, v8
	v_lshl_add_u64 v[20:21], s[14:15], 0, v[4:5]
	s_mov_b64 s[4:5], 0x6120000
	v_lshl_add_u64 v[10:11], v[20:21], 0, s[4:5]
	s_mov_b64 s[4:5], 0x5b20000
	s_add_u32 s16, s14, 0x1400000
	v_lshl_add_u64 v[12:13], v[20:21], 0, s[4:5]
	s_mov_b64 s[4:5], 0x5920000
	s_addc_u32 s17, s15, 0
	s_lshl_b32 s2, s20, 14
	v_lshl_add_u64 v[14:15], v[20:21], 0, s[4:5]
	s_mov_b64 s[4:5], 0x58e0000
	s_add_i32 s2, s2, 0
	v_lshrrev_b32_e32 v7, 3, v28
	v_lshl_add_u64 v[16:17], v[20:21], 0, s[4:5]
	s_mov_b64 s[4:5], 0x5880000
	v_lshrrev_b32_e32 v2, 5, v28
	v_mul_u32_u24_e32 v1, 0x84, v8
	v_lshlrev_b32_e32 v3, 2, v7
	v_lshl_add_u64 v[18:19], v[20:21], 0, s[4:5]
	s_mov_b64 s[4:5], 0x5600000
	s_add_u32 s19, s14, 0x4000000
	s_mov_b32 s3, 0
	v_lshl_add_u32 v6, v22, 2, s2
	s_movk_i32 s18, 0x84
	v_add3_u32 v9, s2, v1, v3
	v_or_b32_e32 v27, 8, v7
	v_or_b32_e32 v28, 16, v7
	v_or_b32_e32 v29, 24, v7
	v_lshl_add_u64 v[20:21], v[20:21], 0, s[4:5]
	s_addc_u32 s20, s15, 0
	v_mov_b32_e32 v1, v2
	s_movk_i32 s21, 0x3000
	s_movk_i32 s22, 0xc00
	s_movk_i32 s23, 0x1280
	s_movk_i32 s24, 0x48
	s_movk_i32 s25, 0xc0
	s_movk_i32 s26, 0x2c00
	v_lshlrev_b32_e32 v22, 2, v22
	s_branch .LBB0_47
